# v18: attention loop: DMA issue, slot rotation and V-fragment prefetch moved into the QK MFMA gaps; V fragments read 8 MFMAs ahead
# speedup vs baseline: 1.0481x; 1.0164x over previous
.Lat_noqk1_2:
	s_mov_b32 s5, 1
	s_mov_b32 s12, 16384
	s_mov_b32 s84, 32768
	v_add_u32_e32 v215, s84, v161
	v_add_u32_e32 v165, s84, v162
	v_add_u32_e32 v216, s84, v163
	v_add_u32_e32 v217, s84, v164
	ds_read_b64_tr_b16 v[224:225], v215 offset:0
	ds_read_b64_tr_b16 v[226:227], v215 offset:2048
	ds_read_b64_tr_b16 v[228:229], v165 offset:0
	ds_read_b64_tr_b16 v[230:231], v165 offset:2048
	ds_read_b64_tr_b16 v[232:233], v216 offset:0
	ds_read_b64_tr_b16 v[234:235], v216 offset:2048
	ds_read_b64_tr_b16 v[236:237], v217 offset:0
	ds_read_b64_tr_b16 v[238:239], v217 offset:2048
	ds_read_b64_tr_b16 v[240:241], v215 offset:4096
	ds_read_b64_tr_b16 v[242:243], v215 offset:6144
	ds_read_b64_tr_b16 v[130:131], v165 offset:4096
	ds_read_b64_tr_b16 v[132:133], v165 offset:6144
	ds_read_b64_tr_b16 v[134:135], v216 offset:4096
	ds_read_b64_tr_b16 v[136:137], v216 offset:6144
	ds_read_b64_tr_b16 v[184:185], v217 offset:4096
	ds_read_b64_tr_b16 v[186:187], v217 offset:6144
	s_waitcnt vmcnt(3) lgkmcnt(15)
	s_barrier
.Lat_loop:
	s_add_i32 s16, s81, 1
	s_cmp_gt_i32 s5, s16
	s_cbranch_scc1 .Lat_xdone_3
	v_add_u32_e32 v188, s12, v157
	v_add_u32_e32 v189, s12, v158
	v_add_u32_e32 v222, s12, v159
	v_add_u32_e32 v223, s12, v160
	s_cmp_gt_i32 s5, s81
	s_cbranch_scc1 .Lat_pvonly_4
	s_waitcnt lgkmcnt(14)
	v_mfma_f32_32x32x16_bf16 v[0:15], v[224:227], v[114:117], v[0:15]
	v_exp_f32_e32 v82, v82
	v_exp_f32_e32 v83, v83
	v_mov_b32_e32 v180, 0
	ds_read_b64_tr_b16 v[224:225], v215 offset:8192
	ds_read_b64_tr_b16 v[226:227], v215 offset:10240
	s_waitcnt lgkmcnt(14)
	v_mfma_f32_32x32x16_bf16 v[16:31], v[228:231], v[114:117], v[16:31]
	v_exp_f32_e32 v84, v84
	v_exp_f32_e32 v85, v85
	v_add_f32_e32 v180, v180, v82
	v_add_f32_e32 v180, v180, v83
	ds_read_b64_tr_b16 v[228:229], v165 offset:8192
	ds_read_b64_tr_b16 v[230:231], v165 offset:10240
	s_waitcnt lgkmcnt(14)
	v_mfma_f32_32x32x16_bf16 v[32:47], v[232:235], v[114:117], v[32:47]
	v_exp_f32_e32 v86, v86
	v_exp_f32_e32 v87, v87
	v_add_f32_e32 v180, v180, v84
	v_add_f32_e32 v180, v180, v85
	ds_read_b64_tr_b16 v[232:233], v216 offset:8192
	ds_read_b64_tr_b16 v[234:235], v216 offset:10240
	s_waitcnt lgkmcnt(14)
	v_mfma_f32_32x32x16_bf16 v[48:63], v[236:239], v[114:117], v[48:63]
	v_exp_f32_e32 v88, v88
	v_exp_f32_e32 v89, v89
	v_add_f32_e32 v180, v180, v86
	v_add_f32_e32 v180, v180, v87
	ds_read_b64_tr_b16 v[236:237], v217 offset:8192
	ds_read_b64_tr_b16 v[238:239], v217 offset:10240
	s_waitcnt lgkmcnt(14)
	v_mfma_f32_32x32x16_bf16 v[0:15], v[240:243], v[118:121], v[0:15]
	v_exp_f32_e32 v90, v90
	v_exp_f32_e32 v91, v91
	v_add_f32_e32 v180, v180, v88
	v_add_f32_e32 v180, v180, v89
	v_cvt_pk_bf16_f32 v114, v82, v83
	ds_read_b64_tr_b16 v[240:241], v215 offset:12288
	ds_read_b64_tr_b16 v[242:243], v215 offset:14336
	s_waitcnt lgkmcnt(14)
	v_mfma_f32_32x32x16_bf16 v[16:31], v[130:133], v[118:121], v[16:31]
	v_exp_f32_e32 v92, v92
	v_exp_f32_e32 v93, v93
	v_add_f32_e32 v180, v180, v90
	v_add_f32_e32 v180, v180, v91
	v_cvt_pk_bf16_f32 v115, v84, v85
	ds_read_b64_tr_b16 v[130:131], v165 offset:12288
	ds_read_b64_tr_b16 v[132:133], v165 offset:14336
	s_waitcnt lgkmcnt(14)
	v_mfma_f32_32x32x16_bf16 v[32:47], v[134:137], v[118:121], v[32:47]
	v_exp_f32_e32 v94, v94
	v_exp_f32_e32 v95, v95
	v_add_f32_e32 v180, v180, v92
	v_add_f32_e32 v180, v180, v93
	v_cvt_pk_bf16_f32 v116, v86, v87
	ds_read_b64_tr_b16 v[134:135], v216 offset:12288
	ds_read_b64_tr_b16 v[136:137], v216 offset:14336
	s_waitcnt lgkmcnt(14)
	v_mfma_f32_32x32x16_bf16 v[48:63], v[184:187], v[118:121], v[48:63]
	v_exp_f32_e32 v96, v96
	v_exp_f32_e32 v97, v97
	v_add_f32_e32 v180, v180, v94
	v_add_f32_e32 v180, v180, v95
	v_cvt_pk_bf16_f32 v117, v88, v89
	ds_read_b64_tr_b16 v[184:185], v217 offset:12288
	ds_read_b64_tr_b16 v[186:187], v217 offset:14336
	s_waitcnt lgkmcnt(14)
	v_mfma_f32_32x32x16_bf16 v[0:15], v[224:227], v[122:125], v[0:15]
	v_exp_f32_e32 v98, v98
	v_exp_f32_e32 v99, v99
	v_add_f32_e32 v180, v180, v96
	v_add_f32_e32 v180, v180, v97
	v_cvt_pk_bf16_f32 v118, v90, v91
	s_waitcnt lgkmcnt(12)
	v_mfma_f32_32x32x16_bf16 v[16:31], v[228:231], v[122:125], v[16:31]
	v_exp_f32_e32 v100, v100
	v_exp_f32_e32 v101, v101
	v_add_f32_e32 v180, v180, v98
	v_add_f32_e32 v180, v180, v99
	v_cvt_pk_bf16_f32 v119, v92, v93
	s_waitcnt lgkmcnt(10)
	v_mfma_f32_32x32x16_bf16 v[32:47], v[232:235], v[122:125], v[32:47]
	v_exp_f32_e32 v102, v102
	v_exp_f32_e32 v103, v103
	v_add_f32_e32 v180, v180, v100
	v_add_f32_e32 v180, v180, v101
	v_cvt_pk_bf16_f32 v120, v94, v95
	s_waitcnt lgkmcnt(8)
	v_mfma_f32_32x32x16_bf16 v[48:63], v[236:239], v[122:125], v[48:63]
	v_exp_f32_e32 v104, v104
	v_exp_f32_e32 v105, v105
	v_add_f32_e32 v180, v180, v102
	v_add_f32_e32 v180, v180, v103
	v_cvt_pk_bf16_f32 v121, v96, v97
	ds_read_b128 v[224:227], v188
	ds_read_b128 v[228:231], v188 offset:4096
	ds_read_b128 v[232:235], v189
	ds_read_b128 v[236:239], v189 offset:4096
	s_waitcnt lgkmcnt(10)
	v_mfma_f32_32x32x16_bf16 v[0:15], v[240:243], v[126:129], v[0:15]
	v_exp_f32_e32 v106, v106
	v_exp_f32_e32 v107, v107
	v_add_f32_e32 v180, v180, v104
	v_add_f32_e32 v180, v180, v105
	v_cvt_pk_bf16_f32 v122, v98, v99
	s_waitcnt lgkmcnt(8)
	v_mfma_f32_32x32x16_bf16 v[16:31], v[130:133], v[126:129], v[16:31]
	v_exp_f32_e32 v108, v108
	v_exp_f32_e32 v109, v109
	v_add_f32_e32 v180, v180, v106
	v_add_f32_e32 v180, v180, v107
	v_cvt_pk_bf16_f32 v123, v100, v101
	s_waitcnt lgkmcnt(6)
	v_mfma_f32_32x32x16_bf16 v[32:47], v[134:137], v[126:129], v[32:47]
	v_exp_f32_e32 v110, v110
	v_exp_f32_e32 v111, v111
	v_add_f32_e32 v180, v180, v108
	v_add_f32_e32 v180, v180, v109
	v_cvt_pk_bf16_f32 v124, v102, v103
	s_waitcnt lgkmcnt(4)
	v_mfma_f32_32x32x16_bf16 v[48:63], v[184:187], v[126:129], v[48:63]
	v_exp_f32_e32 v112, v112
	v_exp_f32_e32 v113, v113
	v_add_f32_e32 v180, v180, v110
	v_add_f32_e32 v180, v180, v111
	v_cvt_pk_bf16_f32 v125, v104, v105
	s_nop 0
	v_add_f32_e32 v180, v180, v112
	v_add_f32_e32 v180, v180, v113
	v_cvt_pk_bf16_f32 v126, v106, v107
	v_cvt_pk_bf16_f32 v127, v108, v109
	v_cvt_pk_bf16_f32 v128, v110, v111
	v_cvt_pk_bf16_f32 v129, v112, v113
	v_cmp_ngt_f32_e32 vcc, s23, v180
	s_cbranch_vccz .Lat_norescale_5
	ds_bpermute_b32 v182, v214, v180
	s_waitcnt lgkmcnt(0)
	v_add_f32_e32 v182, v180, v182
	v_min_f32_e32 v182, 0x7f61b1e6, v182
	v_log_f32_e32 v182, v182
	s_nop 0
	v_floor_f32_e32 v182, v182
	v_max_f32_e32 v182, 0, v182
	v_exp_f32_e64 v183, -v182
	v_add_f32_e32 v80, v80, v182
	v_mul_f32_e32 v81, v81, v183
	v_mul_f32_e32 v180, v180, v183
	v_xor_b32_e32 v64, 0x80000000, v80
	v_mov_b32_e32 v65, v64
	v_mov_b32_e32 v66, v64
	v_mov_b32_e32 v67, v64
	v_mov_b32_e32 v68, v64
	v_mov_b32_e32 v69, v64
	v_mov_b32_e32 v70, v64
	v_mov_b32_e32 v71, v64
	v_mov_b32_e32 v72, v64
	v_mov_b32_e32 v73, v64
	v_mov_b32_e32 v74, v64
	v_mov_b32_e32 v75, v64
	v_mov_b32_e32 v76, v64
	v_mov_b32_e32 v77, v64
	v_mov_b32_e32 v78, v64
	v_mov_b32_e32 v79, v64
	v_mul_f32_e32 v82, v82, v183
	v_mul_f32_e32 v83, v83, v183
	v_mul_f32_e32 v84, v84, v183
	v_mul_f32_e32 v85, v85, v183
	v_mul_f32_e32 v86, v86, v183
	v_mul_f32_e32 v87, v87, v183
	v_mul_f32_e32 v88, v88, v183
	v_mul_f32_e32 v89, v89, v183
	v_mul_f32_e32 v90, v90, v183
	v_mul_f32_e32 v91, v91, v183
	v_mul_f32_e32 v92, v92, v183
	v_mul_f32_e32 v93, v93, v183
	v_mul_f32_e32 v94, v94, v183
	v_mul_f32_e32 v95, v95, v183
	v_mul_f32_e32 v96, v96, v183
	v_mul_f32_e32 v97, v97, v183
	v_mul_f32_e32 v98, v98, v183
	v_mul_f32_e32 v99, v99, v183
	v_mul_f32_e32 v100, v100, v183
	v_mul_f32_e32 v101, v101, v183
	v_mul_f32_e32 v102, v102, v183
	v_mul_f32_e32 v103, v103, v183
	v_mul_f32_e32 v104, v104, v183
	v_mul_f32_e32 v105, v105, v183
	v_mul_f32_e32 v106, v106, v183
	v_mul_f32_e32 v107, v107, v183
	v_mul_f32_e32 v108, v108, v183
	v_mul_f32_e32 v109, v109, v183
	v_mul_f32_e32 v110, v110, v183
	v_mul_f32_e32 v111, v111, v183
	v_mul_f32_e32 v112, v112, v183
	v_mul_f32_e32 v113, v113, v183
	v_mul_f32_e32 v0, v0, v183
	v_mul_f32_e32 v1, v1, v183
	v_mul_f32_e32 v2, v2, v183
	v_mul_f32_e32 v3, v3, v183
	v_mul_f32_e32 v4, v4, v183
	v_mul_f32_e32 v5, v5, v183
	v_mul_f32_e32 v6, v6, v183
	v_mul_f32_e32 v7, v7, v183
	v_mul_f32_e32 v8, v8, v183
	v_mul_f32_e32 v9, v9, v183
	v_mul_f32_e32 v10, v10, v183
	v_mul_f32_e32 v11, v11, v183
	v_mul_f32_e32 v12, v12, v183
	v_mul_f32_e32 v13, v13, v183
	v_mul_f32_e32 v14, v14, v183
	v_mul_f32_e32 v15, v15, v183
	v_mul_f32_e32 v16, v16, v183
	v_mul_f32_e32 v17, v17, v183
	v_mul_f32_e32 v18, v18, v183
	v_mul_f32_e32 v19, v19, v183
	v_mul_f32_e32 v20, v20, v183
	v_mul_f32_e32 v21, v21, v183
	v_mul_f32_e32 v22, v22, v183
	v_mul_f32_e32 v23, v23, v183
	v_mul_f32_e32 v24, v24, v183
	v_mul_f32_e32 v25, v25, v183
	v_mul_f32_e32 v26, v26, v183
	v_mul_f32_e32 v27, v27, v183
	v_mul_f32_e32 v28, v28, v183
	v_mul_f32_e32 v29, v29, v183
	v_mul_f32_e32 v30, v30, v183
	v_mul_f32_e32 v31, v31, v183
	v_mul_f32_e32 v32, v32, v183
	v_mul_f32_e32 v33, v33, v183
	v_mul_f32_e32 v34, v34, v183
	v_mul_f32_e32 v35, v35, v183
	v_mul_f32_e32 v36, v36, v183
	v_mul_f32_e32 v37, v37, v183
	v_mul_f32_e32 v38, v38, v183
	v_mul_f32_e32 v39, v39, v183
	v_mul_f32_e32 v40, v40, v183
	v_mul_f32_e32 v41, v41, v183
	v_mul_f32_e32 v42, v42, v183
	v_mul_f32_e32 v43, v43, v183
	v_mul_f32_e32 v44, v44, v183
	v_mul_f32_e32 v45, v45, v183
	v_mul_f32_e32 v46, v46, v183
	v_mul_f32_e32 v47, v47, v183
	v_mul_f32_e32 v48, v48, v183
	v_mul_f32_e32 v49, v49, v183
	v_mul_f32_e32 v50, v50, v183
	v_mul_f32_e32 v51, v51, v183
	v_mul_f32_e32 v52, v52, v183
	v_mul_f32_e32 v53, v53, v183
	v_mul_f32_e32 v54, v54, v183
	v_mul_f32_e32 v55, v55, v183
	v_mul_f32_e32 v56, v56, v183
	v_mul_f32_e32 v57, v57, v183
	v_mul_f32_e32 v58, v58, v183
	v_mul_f32_e32 v59, v59, v183
	v_mul_f32_e32 v60, v60, v183
	v_mul_f32_e32 v61, v61, v183
	v_mul_f32_e32 v62, v62, v183
	v_mul_f32_e32 v63, v63, v183
	v_cvt_pk_bf16_f32 v114, v82, v83
	v_cvt_pk_bf16_f32 v115, v84, v85
	v_cvt_pk_bf16_f32 v116, v86, v87
	v_cvt_pk_bf16_f32 v117, v88, v89
	v_cvt_pk_bf16_f32 v118, v90, v91
	v_cvt_pk_bf16_f32 v119, v92, v93
	v_cvt_pk_bf16_f32 v120, v94, v95
	v_cvt_pk_bf16_f32 v121, v96, v97
	v_cvt_pk_bf16_f32 v122, v98, v99
	v_cvt_pk_bf16_f32 v123, v100, v101
	v_cvt_pk_bf16_f32 v124, v102, v103
	v_cvt_pk_bf16_f32 v125, v104, v105
	v_cvt_pk_bf16_f32 v126, v106, v107
	v_cvt_pk_bf16_f32 v127, v108, v109
	v_cvt_pk_bf16_f32 v128, v110, v111
	v_cvt_pk_bf16_f32 v129, v112, v113

.Lat_pvonly_4:
	s_waitcnt lgkmcnt(14)
	v_mfma_f32_32x32x16_bf16 v[0:15], v[224:227], v[114:117], v[0:15]
	ds_read_b64_tr_b16 v[224:225], v215 offset:8192
	ds_read_b64_tr_b16 v[226:227], v215 offset:10240
	s_waitcnt lgkmcnt(14)
	v_mfma_f32_32x32x16_bf16 v[16:31], v[228:231], v[114:117], v[16:31]
	ds_read_b64_tr_b16 v[228:229], v165 offset:8192
	ds_read_b64_tr_b16 v[230:231], v165 offset:10240
	s_waitcnt lgkmcnt(14)
	v_mfma_f32_32x32x16_bf16 v[32:47], v[232:235], v[114:117], v[32:47]
	ds_read_b64_tr_b16 v[232:233], v216 offset:8192
	ds_read_b64_tr_b16 v[234:235], v216 offset:10240
	s_waitcnt lgkmcnt(14)
	v_mfma_f32_32x32x16_bf16 v[48:63], v[236:239], v[114:117], v[48:63]
	ds_read_b64_tr_b16 v[236:237], v217 offset:8192
	ds_read_b64_tr_b16 v[238:239], v217 offset:10240
	s_waitcnt lgkmcnt(14)
	v_mfma_f32_32x32x16_bf16 v[0:15], v[240:243], v[118:121], v[0:15]
	ds_read_b64_tr_b16 v[240:241], v215 offset:12288
	ds_read_b64_tr_b16 v[242:243], v215 offset:14336
	s_waitcnt lgkmcnt(14)
	v_mfma_f32_32x32x16_bf16 v[16:31], v[130:133], v[118:121], v[16:31]
	ds_read_b64_tr_b16 v[130:131], v165 offset:12288
	ds_read_b64_tr_b16 v[132:133], v165 offset:14336
	s_waitcnt lgkmcnt(14)
	v_mfma_f32_32x32x16_bf16 v[32:47], v[134:137], v[118:121], v[32:47]
	ds_read_b64_tr_b16 v[134:135], v216 offset:12288
	ds_read_b64_tr_b16 v[136:137], v216 offset:14336
	s_waitcnt lgkmcnt(14)
	v_mfma_f32_32x32x16_bf16 v[48:63], v[184:187], v[118:121], v[48:63]
	ds_read_b64_tr_b16 v[184:185], v217 offset:12288
	ds_read_b64_tr_b16 v[186:187], v217 offset:14336
	s_waitcnt lgkmcnt(14)
	v_mfma_f32_32x32x16_bf16 v[0:15], v[224:227], v[122:125], v[0:15]
	s_waitcnt lgkmcnt(12)
	v_mfma_f32_32x32x16_bf16 v[16:31], v[228:231], v[122:125], v[16:31]
	s_waitcnt lgkmcnt(10)
	v_mfma_f32_32x32x16_bf16 v[32:47], v[232:235], v[122:125], v[32:47]
	s_waitcnt lgkmcnt(8)
	v_mfma_f32_32x32x16_bf16 v[48:63], v[236:239], v[122:125], v[48:63]
	s_waitcnt lgkmcnt(6)
	v_mfma_f32_32x32x16_bf16 v[0:15], v[240:243], v[126:129], v[0:15]
	s_waitcnt lgkmcnt(4)
	v_mfma_f32_32x32x16_bf16 v[16:31], v[130:133], v[126:129], v[16:31]
	s_waitcnt lgkmcnt(2)
	v_mfma_f32_32x32x16_bf16 v[32:47], v[134:137], v[126:129], v[32:47]
	s_waitcnt lgkmcnt(0)
	v_mfma_f32_32x32x16_bf16 v[48:63], v[184:187], v[126:129], v[48:63]
.Lat_xdone_3:
	s_add_i32 s8, s5, 1
	s_cmp_gt_i32 s8, s81
	s_cbranch_scc1 .Lat_noqk_6
	ds_read_b128 v[240:243], v222
	ds_read_b128 v[130:133], v222 offset:4096
	ds_read_b128 v[134:137], v223
	ds_read_b128 v[184:187], v223 offset:4096
	s_waitcnt lgkmcnt(7)
	v_mfma_f32_32x32x16_bf16 v[82:97], v[224:227], v[150:153], v[64:79]
	s_add_i32 m0, s13, s68
	s_nop 0
	global_load_lds_dwordx4 v154, s[14:15]
	s_waitcnt lgkmcnt(6)
	v_mfma_f32_32x32x16_bf16 v[98:113], v[228:231], v[150:153], v[64:79]
	s_add_i32 m0, s17, s69
	s_nop 0
	global_load_lds_dwordx4 v155, s[18:19]
	s_waitcnt lgkmcnt(5)
	v_mfma_f32_32x32x16_bf16 v[82:97], v[232:235], v[146:149], v[82:97]
	s_add_i32 m0, m0, 0x400
	s_nop 0
	global_load_lds_dwordx4 v156, s[18:19]
	s_waitcnt lgkmcnt(4)
	v_mfma_f32_32x32x16_bf16 v[98:113], v[236:239], v[146:149], v[98:113]
	s_add_i32 s13, s13, 8192
	s_cmp_eq_u32 s13, 32768
	s_cselect_b32 s13, 0, s13
	s_add_i32 s17, s17, 16384
	s_cmp_eq_u32 s17, 114688
	s_cselect_b32 s17, 32768, s17
	s_add_i32 s85, s85, 1
	s_cmp_lt_u32 s85, s6
	s_cselect_b32 s8, 0x40000, 0
	s_add_u32 s14, s14, s8
	s_addc_u32 s15, s15, 0
	s_add_u32 s18, s18, s8
	s_addc_u32 s19, s19, 0
	s_add_i32 s5, s5, 1
	s_add_i32 s12, s12, 8192
	s_cmp_eq_u32 s12, 32768
	s_cselect_b32 s12, 0, s12
	s_add_i32 s84, s84, 16384
	s_cmp_eq_u32 s84, 114688
	s_cselect_b32 s84, 32768, s84
	s_waitcnt lgkmcnt(3)
	v_mfma_f32_32x32x16_bf16 v[82:97], v[240:243], v[142:145], v[82:97]
	v_add_u32_e32 v215, s84, v161
	v_add_u32_e32 v165, s84, v162
	v_add_u32_e32 v216, s84, v163
	v_add_u32_e32 v217, s84, v164
	ds_read_b64_tr_b16 v[224:225], v215 offset:0
	ds_read_b64_tr_b16 v[226:227], v215 offset:2048
	s_waitcnt lgkmcnt(4)
	v_mfma_f32_32x32x16_bf16 v[98:113], v[130:133], v[142:145], v[98:113]
	ds_read_b64_tr_b16 v[228:229], v165 offset:0
	ds_read_b64_tr_b16 v[230:231], v165 offset:2048
	ds_read_b64_tr_b16 v[232:233], v216 offset:0
	ds_read_b64_tr_b16 v[234:235], v216 offset:2048
	s_waitcnt lgkmcnt(7)
	v_mfma_f32_32x32x16_bf16 v[82:97], v[134:137], v[138:141], v[82:97]
	ds_read_b64_tr_b16 v[236:237], v217 offset:0
	ds_read_b64_tr_b16 v[238:239], v217 offset:2048
	s_waitcnt lgkmcnt(8)
	v_mfma_f32_32x32x16_bf16 v[98:113], v[184:187], v[138:141], v[98:113]
	ds_read_b64_tr_b16 v[240:241], v215 offset:4096
	ds_read_b64_tr_b16 v[242:243], v215 offset:6144
	ds_read_b64_tr_b16 v[130:131], v165 offset:4096
	ds_read_b64_tr_b16 v[132:133], v165 offset:6144
	ds_read_b64_tr_b16 v[134:135], v216 offset:4096
	ds_read_b64_tr_b16 v[136:137], v216 offset:6144
	ds_read_b64_tr_b16 v[184:185], v217 offset:4096
	ds_read_b64_tr_b16 v[186:187], v217 offset:6144
	s_waitcnt vmcnt(3) lgkmcnt(15)
	s_branch .Lat_bottom_7
.Lat_noqk_6:
	s_add_i32 m0, s13, s68
	s_nop 0
	global_load_lds_dwordx4 v154, s[14:15]
	s_add_i32 m0, s17, s69
	s_nop 0
	global_load_lds_dwordx4 v155, s[18:19]
	s_add_i32 m0, m0, 0x400
	s_nop 0
	global_load_lds_dwordx4 v156, s[18:19]
	s_add_i32 s13, s13, 8192
	s_cmp_eq_u32 s13, 32768
	s_cselect_b32 s13, 0, s13
	s_add_i32 s17, s17, 16384
	s_cmp_eq_u32 s17, 114688
	s_cselect_b32 s17, 32768, s17
	s_add_i32 s85, s85, 1
	s_cmp_lt_u32 s85, s6
	s_cselect_b32 s8, 0x40000, 0
	s_add_u32 s14, s14, s8
	s_addc_u32 s15, s15, 0
	s_add_u32 s18, s18, s8
	s_addc_u32 s19, s19, 0
	s_add_i32 s5, s5, 1
	s_add_i32 s12, s12, 8192
	s_cmp_eq_u32 s12, 32768
	s_cselect_b32 s12, 0, s12
	s_add_i32 s84, s84, 16384
	s_cmp_eq_u32 s84, 114688
	s_cselect_b32 s84, 32768, s84
	s_add_i32 s16, s81, 1
	s_cmp_gt_i32 s5, s16
	s_cbranch_scc1 .Lat_novpre_8
	v_add_u32_e32 v215, s84, v161
	v_add_u32_e32 v165, s84, v162
	v_add_u32_e32 v216, s84, v163
	v_add_u32_e32 v217, s84, v164
	ds_read_b64_tr_b16 v[224:225], v215 offset:0
	ds_read_b64_tr_b16 v[226:227], v215 offset:2048
	ds_read_b64_tr_b16 v[228:229], v165 offset:0
	ds_read_b64_tr_b16 v[230:231], v165 offset:2048
	ds_read_b64_tr_b16 v[232:233], v216 offset:0
	ds_read_b64_tr_b16 v[234:235], v216 offset:2048
	ds_read_b64_tr_b16 v[236:237], v217 offset:0
	ds_read_b64_tr_b16 v[238:239], v217 offset:2048
	ds_read_b64_tr_b16 v[240:241], v215 offset:4096
	ds_read_b64_tr_b16 v[242:243], v215 offset:6144
	ds_read_b64_tr_b16 v[130:131], v165 offset:4096
	ds_read_b64_tr_b16 v[132:133], v165 offset:6144
	ds_read_b64_tr_b16 v[134:135], v216 offset:4096
	ds_read_b64_tr_b16 v[136:137], v216 offset:6144
	ds_read_b64_tr_b16 v[184:185], v217 offset:4096
	ds_read_b64_tr_b16 v[186:187], v217 offset:6144
	s_waitcnt vmcnt(3) lgkmcnt(15)
	s_branch .Lat_bottom_7

.Lat_bottom_7:
	s_barrier
	s_cmp_lt_u32 s5, s6
	s_cbranch_scc1 .Lat_loop
	s_add_i32 s16, s81, 1
	s_cmp_gt_i32 s5, s16
	s_cbranch_scc1 .Lat_nolast_9
	s_waitcnt lgkmcnt(14)
	v_mfma_f32_32x32x16_bf16 v[0:15], v[224:227], v[114:117], v[0:15]
	ds_read_b64_tr_b16 v[224:225], v215 offset:8192
	ds_read_b64_tr_b16 v[226:227], v215 offset:10240
	s_waitcnt lgkmcnt(14)
	v_mfma_f32_32x32x16_bf16 v[16:31], v[228:231], v[114:117], v[16:31]
	ds_read_b64_tr_b16 v[228:229], v165 offset:8192
	ds_read_b64_tr_b16 v[230:231], v165 offset:10240
	s_waitcnt lgkmcnt(14)
	v_mfma_f32_32x32x16_bf16 v[32:47], v[232:235], v[114:117], v[32:47]
	ds_read_b64_tr_b16 v[232:233], v216 offset:8192
	ds_read_b64_tr_b16 v[234:235], v216 offset:10240
	s_waitcnt lgkmcnt(14)
	v_mfma_f32_32x32x16_bf16 v[48:63], v[236:239], v[114:117], v[48:63]
	ds_read_b64_tr_b16 v[236:237], v217 offset:8192
	ds_read_b64_tr_b16 v[238:239], v217 offset:10240
	s_waitcnt lgkmcnt(14)
	v_mfma_f32_32x32x16_bf16 v[0:15], v[240:243], v[118:121], v[0:15]
	ds_read_b64_tr_b16 v[240:241], v215 offset:12288
	ds_read_b64_tr_b16 v[242:243], v215 offset:14336
	s_waitcnt lgkmcnt(14)
	v_mfma_f32_32x32x16_bf16 v[16:31], v[130:133], v[118:121], v[16:31]
	ds_read_b64_tr_b16 v[130:131], v165 offset:12288
	ds_read_b64_tr_b16 v[132:133], v165 offset:14336
	s_waitcnt lgkmcnt(14)
	v_mfma_f32_32x32x16_bf16 v[32:47], v[134:137], v[118:121], v[32:47]
	ds_read_b64_tr_b16 v[134:135], v216 offset:12288
	ds_read_b64_tr_b16 v[136:137], v216 offset:14336
	s_waitcnt lgkmcnt(14)
	v_mfma_f32_32x32x16_bf16 v[48:63], v[184:187], v[118:121], v[48:63]
	ds_read_b64_tr_b16 v[184:185], v217 offset:12288
	ds_read_b64_tr_b16 v[186:187], v217 offset:14336
	s_waitcnt lgkmcnt(14)
	v_mfma_f32_32x32x16_bf16 v[0:15], v[224:227], v[122:125], v[0:15]
	s_waitcnt lgkmcnt(12)
	v_mfma_f32_32x32x16_bf16 v[16:31], v[228:231], v[122:125], v[16:31]
	s_waitcnt lgkmcnt(10)
	v_mfma_f32_32x32x16_bf16 v[32:47], v[232:235], v[122:125], v[32:47]
	s_waitcnt lgkmcnt(8)
	v_mfma_f32_32x32x16_bf16 v[48:63], v[236:239], v[122:125], v[48:63]
	s_waitcnt lgkmcnt(6)
	v_mfma_f32_32x32x16_bf16 v[0:15], v[240:243], v[126:129], v[0:15]
	s_waitcnt lgkmcnt(4)
	v_mfma_f32_32x32x16_bf16 v[16:31], v[130:133], v[126:129], v[16:31]
	s_waitcnt lgkmcnt(2)
	v_mfma_f32_32x32x16_bf16 v[32:47], v[134:137], v[126:129], v[32:47]
	s_waitcnt lgkmcnt(0)
	v_mfma_f32_32x32x16_bf16 v[48:63], v[184:187], v[126:129], v[48:63]
